# first grid barrier: 16 census counters read together instead of one per vmcnt(0); plus all earlier edits
# baseline (speedup 1.0000x reference)
; __device__ __forceinline__ unsigned xb_ld(unsigned* p)              { return __hip_atomic_load(p, __ATOMIC_RELAXED, __HIP_MEMORY_SCOPE_AGENT); }
; __device__ __forceinline__ void xcd_barrier_complete(unsigned* bar, unsigned x, unsigned& nloc, unsigned& nx) {
;     const unsigned G = gridDim.x * gridDim.y * gridDim.z;
;     unsigned sum, cnt, mine, sp = 0u;
;     for (;;) {
;         sum = 0u; cnt = 0u; mine = 0u;
; #pragma unroll
;         for (unsigned j = 0; j < 16; ++j) { const unsigned c = xb_ld(&bar[XB_XCNT(j)]); sum += c; cnt += (c > 0u) ? 1u : 0u; mine = (j == x) ? c : mine; }
;         if (sum == G) break;
;         __builtin_amdgcn_s_sleep(1);
;         if ((++sp & 255u) == 0u) { if (xb_ld(&bar[XB_TMO])) break; if (sp > XB_SPIN_CAP) { atomicAdd(&bar[XB_TMO], 1u); break; } }
;     }
.LBB0_15:
	v_readlane_b32 s6, v252, 13
	v_readlane_b32 s7, v252, 14
	s_mov_b64 s[12:13], -1
	s_mov_b64 s[20:21], -1
	s_nop 2
	global_load_dword v1, v0, s[6:7] sc1
	v_readlane_b32 s6, v252, 15
	v_readlane_b32 s7, v252, 16
	s_nop 4
	global_load_dword v2, v0, s[6:7] sc1
	v_readlane_b32 s6, v252, 17
	v_readlane_b32 s7, v252, 18
	s_nop 1
	s_nop 2
	global_load_dword v3, v0, s[6:7] sc1
	v_readlane_b32 s6, v252, 19
	v_readlane_b32 s7, v252, 20
	s_nop 1
	s_nop 2
	global_load_dword v4, v0, s[6:7] sc1
	v_readlane_b32 s6, v252, 21
	v_readlane_b32 s7, v252, 22
	s_nop 1
	s_nop 2
	global_load_dword v5, v0, s[6:7] sc1
	v_readlane_b32 s6, v252, 23
	v_readlane_b32 s7, v252, 24
	s_nop 1
	s_nop 2
	global_load_dword v6, v0, s[6:7] sc1
	v_readlane_b32 s6, v252, 25
	v_readlane_b32 s7, v252, 26
	s_nop 1
	s_nop 2
	global_load_dword v7, v0, s[6:7] sc1
	v_readlane_b32 s6, v252, 27
	v_readlane_b32 s7, v252, 28
	s_nop 1
	s_nop 2
	global_load_dword v8, v0, s[6:7] sc1
	v_readlane_b32 s6, v252, 29
	v_readlane_b32 s7, v252, 30
	s_nop 1
	s_nop 2
	global_load_dword v9, v0, s[6:7] sc1
	v_readlane_b32 s6, v252, 31
	v_readlane_b32 s7, v252, 32
	s_nop 1
	s_nop 2
	global_load_dword v10, v0, s[6:7] sc1
	v_readlane_b32 s6, v252, 33
	v_readlane_b32 s7, v252, 34
	s_nop 1
	s_nop 2
	global_load_dword v11, v0, s[6:7] sc1
	v_readlane_b32 s6, v252, 35
	v_readlane_b32 s7, v252, 36
	s_nop 1
	s_nop 2
	global_load_dword v12, v0, s[6:7] sc1
	v_readlane_b32 s6, v252, 37
	v_readlane_b32 s7, v252, 38
	s_nop 1
	s_nop 2
	global_load_dword v13, v0, s[6:7] sc1
	v_readlane_b32 s6, v252, 39
	v_readlane_b32 s7, v252, 40
	s_nop 1
	s_nop 2
	global_load_dword v14, v0, s[6:7] sc1
	v_readlane_b32 s6, v252, 41
	v_readlane_b32 s7, v252, 42
	s_nop 1
	s_nop 2
	global_load_dword v15, v0, s[6:7] sc1
	v_readlane_b32 s6, v252, 43
	v_readlane_b32 s7, v252, 44
	s_nop 1
	s_nop 2
	global_load_dword v16, v0, s[6:7] sc1
	s_waitcnt vmcnt(0)
	v_add_u32_e32 v17, v2, v1
	v_add_u32_e32 v17, v17, v3
	v_add_u32_e32 v17, v17, v4
	v_add_u32_e32 v17, v17, v5
	v_add_u32_e32 v17, v17, v6
	v_add_u32_e32 v17, v17, v7
	v_add_u32_e32 v17, v17, v8
	v_add_u32_e32 v17, v17, v9
	v_add_u32_e32 v17, v17, v10
	v_add_u32_e32 v17, v17, v11
	v_add_u32_e32 v17, v17, v12
	v_add_u32_e32 v17, v17, v13
	v_add_u32_e32 v17, v17, v14
	v_add_u32_e32 v17, v17, v15
	v_add_u32_e32 v17, v17, v16
	v_cmp_eq_u32_e32 vcc, s4, v17
	s_cbranch_vccnz .LBB0_14
	s_and_b32 s6, s5, 0xff
	s_cmp_eq_u32 s6, 0
	s_mov_b64 s[30:31], -1
	s_sleep 1
	s_cbranch_scc1 .LBB0_19
	s_and_b64 vcc, exec, s[30:31]
	s_cbranch_vccz .LBB0_14
